# chunk scan rewritten: 256 threads x 2 state elements, all 64 chunk loads in flight, SGPR-advanced bases, decay factors via lane load + v_readlane
# speedup vs baseline: 1.0134x; 1.0011x over previous
.LBB0_434:
	s_and_b64 vcc, exec, s[0:1]
	s_cbranch_vccz .LBB0_1086
	v_writelane_b32 v252, s60, 59
	s_cmp_gt_i32 s60, 0
	s_mov_b64 s[0:1], -1
	v_readlane_b32 s64, v252, 34
	v_readlane_b32 s65, v252, 35
	s_cbranch_scc0 .LBB0_1084
	v_readlane_b32 s0, v252, 59
	s_cmp_gt_i32 s0, 1
	s_mov_b64 s[0:1], -1
	s_cbranch_scc0 .LBB0_1000
	s_add_u32 s22, s72, 0xb495000
	s_addc_u32 s23, s73, 0
	s_add_u32 s76, s72, 0x5194000
	s_addc_u32 s77, s73, 0
	s_add_u32 s24, s72, 0xa415000
	s_addc_u32 s25, s73, 0
	v_readlane_b32 s0, v251, 10
	s_nop 3
	s_lshr_b32 s2, s0, 15
	s_and_b32 s3, s0, 0x7fff
	s_lshr_b32 s4, s3, 13
	s_lshl_b32 s5, s2, 23
	s_lshl_b32 s3, s3, 2
	s_add_u32 s5, s5, s3
	s_add_u32 s22, s22, s5
	s_addc_u32 s23, s23, 0
	s_lshr_b32 s5, s5, 1
	s_add_u32 s24, s24, s5
	s_addc_u32 s25, s25, 0
	s_lshl_b32 s5, s2, 10
	s_lshl_b32 s4, s4, 2
	s_add_u32 s5, s5, s4
	s_add_u32 s76, s76, s5
	s_addc_u32 s77, s77, 0
	v_readlane_b32 s4, v252, 49
	s_nop 3
	s_lshl_b32 s4, s4, 2
	s_add_u32 s4, s4, s2
	s_lshl_b32 s4, s4, 17
	s_add_u32 s4, s4, s3
	s_add_u32 s4, s4, 0x4200000
	s_add_u32 s2, s20, s4
	s_addc_u32 s3, s21, 0
	v_cmp_gt_u32_e32 vcc, 0x100, v202
	s_and_saveexec_b64 s[0:1], vcc
	s_cbranch_execz .LBB0_440
	v_lshlrev_b32_e32 v2, 3, v202
	v_lshlrev_b32_e32 v3, 2, v202
	v_and_b32_e32 v4, 63, v202
	v_lshlrev_b32_e32 v4, 4, v4
	global_load_dword v5, v4, s[76:77]
	v_mov_b32_e32 v8, 0
	v_mov_b32_e32 v9, 0
	global_load_dwordx2 v[16:17], v2, s[22:23] nt
	s_add_u32 s22, s22, 0x20000
	s_addc_u32 s23, s23, 0
	global_load_dwordx2 v[18:19], v2, s[22:23] nt
	s_add_u32 s22, s22, 0x20000
	s_addc_u32 s23, s23, 0
	global_load_dwordx2 v[20:21], v2, s[22:23] nt
	s_add_u32 s22, s22, 0x20000
	s_addc_u32 s23, s23, 0
	global_load_dwordx2 v[22:23], v2, s[22:23] nt
	s_add_u32 s22, s22, 0x20000
	s_addc_u32 s23, s23, 0
	global_load_dwordx2 v[24:25], v2, s[22:23] nt
	s_add_u32 s22, s22, 0x20000
	s_addc_u32 s23, s23, 0
	global_load_dwordx2 v[26:27], v2, s[22:23] nt
	s_add_u32 s22, s22, 0x20000
	s_addc_u32 s23, s23, 0
	global_load_dwordx2 v[28:29], v2, s[22:23] nt
	s_add_u32 s22, s22, 0x20000
	s_addc_u32 s23, s23, 0
	global_load_dwordx2 v[30:31], v2, s[22:23] nt
	s_add_u32 s22, s22, 0x20000
	s_addc_u32 s23, s23, 0
	global_load_dwordx2 v[32:33], v2, s[22:23] nt
	s_add_u32 s22, s22, 0x20000
	s_addc_u32 s23, s23, 0
	global_load_dwordx2 v[34:35], v2, s[22:23] nt
	s_add_u32 s22, s22, 0x20000
	s_addc_u32 s23, s23, 0
	global_load_dwordx2 v[36:37], v2, s[22:23] nt
	s_add_u32 s22, s22, 0x20000
	s_addc_u32 s23, s23, 0
	global_load_dwordx2 v[38:39], v2, s[22:23] nt
	s_add_u32 s22, s22, 0x20000
	s_addc_u32 s23, s23, 0
	global_load_dwordx2 v[40:41], v2, s[22:23] nt
	s_add_u32 s22, s22, 0x20000
	s_addc_u32 s23, s23, 0
	global_load_dwordx2 v[42:43], v2, s[22:23] nt
	s_add_u32 s22, s22, 0x20000
	s_addc_u32 s23, s23, 0
	global_load_dwordx2 v[44:45], v2, s[22:23] nt
	s_add_u32 s22, s22, 0x20000
	s_addc_u32 s23, s23, 0
	global_load_dwordx2 v[46:47], v2, s[22:23] nt
	s_add_u32 s22, s22, 0x20000
	s_addc_u32 s23, s23, 0
	global_load_dwordx2 v[48:49], v2, s[22:23] nt
	s_add_u32 s22, s22, 0x20000
	s_addc_u32 s23, s23, 0
	global_load_dwordx2 v[50:51], v2, s[22:23] nt
	s_add_u32 s22, s22, 0x20000
	s_addc_u32 s23, s23, 0
	global_load_dwordx2 v[52:53], v2, s[22:23] nt
	s_add_u32 s22, s22, 0x20000
	s_addc_u32 s23, s23, 0
	global_load_dwordx2 v[54:55], v2, s[22:23] nt
	s_add_u32 s22, s22, 0x20000
	s_addc_u32 s23, s23, 0
	global_load_dwordx2 v[56:57], v2, s[22:23] nt
	s_add_u32 s22, s22, 0x20000
	s_addc_u32 s23, s23, 0
	global_load_dwordx2 v[58:59], v2, s[22:23] nt
	s_add_u32 s22, s22, 0x20000
	s_addc_u32 s23, s23, 0
	global_load_dwordx2 v[60:61], v2, s[22:23] nt
	s_add_u32 s22, s22, 0x20000
	s_addc_u32 s23, s23, 0
	global_load_dwordx2 v[62:63], v2, s[22:23] nt
	s_add_u32 s22, s22, 0x20000
	s_addc_u32 s23, s23, 0
	global_load_dwordx2 v[64:65], v2, s[22:23] nt
	s_add_u32 s22, s22, 0x20000
	s_addc_u32 s23, s23, 0
	global_load_dwordx2 v[66:67], v2, s[22:23] nt
	s_add_u32 s22, s22, 0x20000
	s_addc_u32 s23, s23, 0
	global_load_dwordx2 v[68:69], v2, s[22:23] nt
	s_add_u32 s22, s22, 0x20000
	s_addc_u32 s23, s23, 0
	global_load_dwordx2 v[70:71], v2, s[22:23] nt
	s_add_u32 s22, s22, 0x20000
	s_addc_u32 s23, s23, 0
	global_load_dwordx2 v[72:73], v2, s[22:23] nt
	s_add_u32 s22, s22, 0x20000
	s_addc_u32 s23, s23, 0
	global_load_dwordx2 v[74:75], v2, s[22:23] nt
	s_add_u32 s22, s22, 0x20000
	s_addc_u32 s23, s23, 0
	global_load_dwordx2 v[76:77], v2, s[22:23] nt
	s_add_u32 s22, s22, 0x20000
	s_addc_u32 s23, s23, 0
	global_load_dwordx2 v[78:79], v2, s[22:23] nt
	s_add_u32 s22, s22, 0x20000
	s_addc_u32 s23, s23, 0
	global_load_dwordx2 v[80:81], v2, s[22:23] nt
	s_add_u32 s22, s22, 0x20000
	s_addc_u32 s23, s23, 0
	global_load_dwordx2 v[82:83], v2, s[22:23] nt
	s_add_u32 s22, s22, 0x20000
	s_addc_u32 s23, s23, 0
	global_load_dwordx2 v[84:85], v2, s[22:23] nt
	s_add_u32 s22, s22, 0x20000
	s_addc_u32 s23, s23, 0
	global_load_dwordx2 v[86:87], v2, s[22:23] nt
	s_add_u32 s22, s22, 0x20000
	s_addc_u32 s23, s23, 0
	global_load_dwordx2 v[88:89], v2, s[22:23] nt
	s_add_u32 s22, s22, 0x20000
	s_addc_u32 s23, s23, 0
	global_load_dwordx2 v[90:91], v2, s[22:23] nt
	s_add_u32 s22, s22, 0x20000
	s_addc_u32 s23, s23, 0
	global_load_dwordx2 v[92:93], v2, s[22:23] nt
	s_add_u32 s22, s22, 0x20000
	s_addc_u32 s23, s23, 0
	global_load_dwordx2 v[94:95], v2, s[22:23] nt
	s_add_u32 s22, s22, 0x20000
	s_addc_u32 s23, s23, 0
	global_load_dwordx2 v[96:97], v2, s[22:23] nt
	s_add_u32 s22, s22, 0x20000
	s_addc_u32 s23, s23, 0
	global_load_dwordx2 v[98:99], v2, s[22:23] nt
	s_add_u32 s22, s22, 0x20000
	s_addc_u32 s23, s23, 0
	global_load_dwordx2 v[100:101], v2, s[22:23] nt
	s_add_u32 s22, s22, 0x20000
	s_addc_u32 s23, s23, 0
	global_load_dwordx2 v[102:103], v2, s[22:23] nt
	s_add_u32 s22, s22, 0x20000
	s_addc_u32 s23, s23, 0
	global_load_dwordx2 v[104:105], v2, s[22:23] nt
	s_add_u32 s22, s22, 0x20000
	s_addc_u32 s23, s23, 0
	global_load_dwordx2 v[106:107], v2, s[22:23] nt
	s_add_u32 s22, s22, 0x20000
	s_addc_u32 s23, s23, 0
	global_load_dwordx2 v[108:109], v2, s[22:23] nt
	s_add_u32 s22, s22, 0x20000
	s_addc_u32 s23, s23, 0
	global_load_dwordx2 v[110:111], v2, s[22:23] nt
	s_add_u32 s22, s22, 0x20000
	s_addc_u32 s23, s23, 0
	global_load_dwordx2 v[112:113], v2, s[22:23] nt
	s_add_u32 s22, s22, 0x20000
	s_addc_u32 s23, s23, 0
	global_load_dwordx2 v[114:115], v2, s[22:23] nt
	s_add_u32 s22, s22, 0x20000
	s_addc_u32 s23, s23, 0
	global_load_dwordx2 v[116:117], v2, s[22:23] nt
	s_add_u32 s22, s22, 0x20000
	s_addc_u32 s23, s23, 0
	global_load_dwordx2 v[118:119], v2, s[22:23] nt
	s_add_u32 s22, s22, 0x20000
	s_addc_u32 s23, s23, 0
	global_load_dwordx2 v[120:121], v2, s[22:23] nt
	s_add_u32 s22, s22, 0x20000
	s_addc_u32 s23, s23, 0
	global_load_dwordx2 v[122:123], v2, s[22:23] nt
	s_add_u32 s22, s22, 0x20000
	s_addc_u32 s23, s23, 0
	global_load_dwordx2 v[124:125], v2, s[22:23] nt
	s_add_u32 s22, s22, 0x20000
	s_addc_u32 s23, s23, 0
	global_load_dwordx2 v[126:127], v2, s[22:23] nt
	s_add_u32 s22, s22, 0x20000
	s_addc_u32 s23, s23, 0
	global_load_dwordx2 v[128:129], v2, s[22:23] nt
	s_add_u32 s22, s22, 0x20000
	s_addc_u32 s23, s23, 0
	global_load_dwordx2 v[130:131], v2, s[22:23] nt
	s_add_u32 s22, s22, 0x20000
	s_addc_u32 s23, s23, 0
	global_load_dwordx2 v[132:133], v2, s[22:23] nt
	s_add_u32 s22, s22, 0x20000
	s_addc_u32 s23, s23, 0
	global_load_dwordx2 v[134:135], v2, s[22:23] nt
	s_add_u32 s22, s22, 0x20000
	s_addc_u32 s23, s23, 0
	global_load_dwordx2 v[136:137], v2, s[22:23] nt
	s_add_u32 s22, s22, 0x20000
	s_addc_u32 s23, s23, 0
	global_load_dwordx2 v[138:139], v2, s[22:23] nt
	s_add_u32 s22, s22, 0x20000
	s_addc_u32 s23, s23, 0
	global_load_dwordx2 v[140:141], v2, s[22:23] nt
	s_add_u32 s22, s22, 0x20000
	s_addc_u32 s23, s23, 0
	global_load_dwordx2 v[142:143], v2, s[22:23] nt
	s_add_u32 s22, s22, 0x20000
	s_addc_u32 s23, s23, 0
	s_waitcnt vmcnt(63)
	v_readlane_b32 s76, v5, 0
	v_cvt_pk_bf16_f32 v12, v8, v9
	global_store_dword v3, v12, s[24:25]
	s_add_u32 s24, s24, 0x10000
	s_addc_u32 s25, s25, 0
	v_fmac_f32_e32 v16, s76, v8
	v_fmac_f32_e32 v17, s76, v9
	v_readlane_b32 s77, v5, 1
	s_waitcnt vmcnt(63)
	v_cvt_pk_bf16_f32 v13, v16, v17
	global_store_dword v3, v13, s[24:25]
	s_add_u32 s24, s24, 0x10000
	s_addc_u32 s25, s25, 0
	v_fmac_f32_e32 v18, s77, v16
	v_fmac_f32_e32 v19, s77, v17
	v_readlane_b32 s76, v5, 2
	s_waitcnt vmcnt(63)
	v_cvt_pk_bf16_f32 v14, v18, v19
	global_store_dword v3, v14, s[24:25]
	s_add_u32 s24, s24, 0x10000
	s_addc_u32 s25, s25, 0
	v_fmac_f32_e32 v20, s76, v18
	v_fmac_f32_e32 v21, s76, v19
	v_readlane_b32 s77, v5, 3
	s_waitcnt vmcnt(63)
	v_cvt_pk_bf16_f32 v15, v20, v21
	global_store_dword v3, v15, s[24:25]
	s_add_u32 s24, s24, 0x10000
	s_addc_u32 s25, s25, 0
	v_fmac_f32_e32 v22, s77, v20
	v_fmac_f32_e32 v23, s77, v21
	v_readlane_b32 s76, v5, 4
	s_waitcnt vmcnt(63)
	v_cvt_pk_bf16_f32 v12, v22, v23
	global_store_dword v3, v12, s[24:25]
	s_add_u32 s24, s24, 0x10000
	s_addc_u32 s25, s25, 0
	v_fmac_f32_e32 v24, s76, v22
	v_fmac_f32_e32 v25, s76, v23
	v_readlane_b32 s77, v5, 5
	s_waitcnt vmcnt(63)
	v_cvt_pk_bf16_f32 v13, v24, v25
	global_store_dword v3, v13, s[24:25]
	s_add_u32 s24, s24, 0x10000
	s_addc_u32 s25, s25, 0
	v_fmac_f32_e32 v26, s77, v24
	v_fmac_f32_e32 v27, s77, v25
	v_readlane_b32 s76, v5, 6
	s_waitcnt vmcnt(63)
	v_cvt_pk_bf16_f32 v14, v26, v27
	global_store_dword v3, v14, s[24:25]
	s_add_u32 s24, s24, 0x10000
	s_addc_u32 s25, s25, 0
	v_fmac_f32_e32 v28, s76, v26
	v_fmac_f32_e32 v29, s76, v27
	v_readlane_b32 s77, v5, 7
	s_waitcnt vmcnt(63)
	v_cvt_pk_bf16_f32 v15, v28, v29
	global_store_dword v3, v15, s[24:25]
	s_add_u32 s24, s24, 0x10000
	s_addc_u32 s25, s25, 0
	v_fmac_f32_e32 v30, s77, v28
	v_fmac_f32_e32 v31, s77, v29
	v_readlane_b32 s76, v5, 8
	s_waitcnt vmcnt(63)
	v_cvt_pk_bf16_f32 v12, v30, v31
	global_store_dword v3, v12, s[24:25]
	s_add_u32 s24, s24, 0x10000
	s_addc_u32 s25, s25, 0
	v_fmac_f32_e32 v32, s76, v30
	v_fmac_f32_e32 v33, s76, v31
	v_readlane_b32 s77, v5, 9
	s_waitcnt vmcnt(63)
	v_cvt_pk_bf16_f32 v13, v32, v33
	global_store_dword v3, v13, s[24:25]
	s_add_u32 s24, s24, 0x10000
	s_addc_u32 s25, s25, 0
	v_fmac_f32_e32 v34, s77, v32
	v_fmac_f32_e32 v35, s77, v33
	v_readlane_b32 s76, v5, 10
	s_waitcnt vmcnt(63)
	v_cvt_pk_bf16_f32 v14, v34, v35
	global_store_dword v3, v14, s[24:25]
	s_add_u32 s24, s24, 0x10000
	s_addc_u32 s25, s25, 0
	v_fmac_f32_e32 v36, s76, v34
	v_fmac_f32_e32 v37, s76, v35
	v_readlane_b32 s77, v5, 11
	s_waitcnt vmcnt(63)
	v_cvt_pk_bf16_f32 v15, v36, v37
	global_store_dword v3, v15, s[24:25]
	s_add_u32 s24, s24, 0x10000
	s_addc_u32 s25, s25, 0
	v_fmac_f32_e32 v38, s77, v36
	v_fmac_f32_e32 v39, s77, v37
	v_readlane_b32 s76, v5, 12
	s_waitcnt vmcnt(63)
	v_cvt_pk_bf16_f32 v12, v38, v39
	global_store_dword v3, v12, s[24:25]
	s_add_u32 s24, s24, 0x10000
	s_addc_u32 s25, s25, 0
	v_fmac_f32_e32 v40, s76, v38
	v_fmac_f32_e32 v41, s76, v39
	v_readlane_b32 s77, v5, 13
	s_waitcnt vmcnt(63)
	v_cvt_pk_bf16_f32 v13, v40, v41
	global_store_dword v3, v13, s[24:25]
	s_add_u32 s24, s24, 0x10000
	s_addc_u32 s25, s25, 0
	v_fmac_f32_e32 v42, s77, v40
	v_fmac_f32_e32 v43, s77, v41
	v_readlane_b32 s76, v5, 14
	s_waitcnt vmcnt(63)
	v_cvt_pk_bf16_f32 v14, v42, v43
	global_store_dword v3, v14, s[24:25]
	s_add_u32 s24, s24, 0x10000
	s_addc_u32 s25, s25, 0
	v_fmac_f32_e32 v44, s76, v42
	v_fmac_f32_e32 v45, s76, v43
	v_readlane_b32 s77, v5, 15
	s_waitcnt vmcnt(63)
	v_cvt_pk_bf16_f32 v15, v44, v45
	global_store_dword v3, v15, s[24:25]
	s_add_u32 s24, s24, 0x10000
	s_addc_u32 s25, s25, 0
	v_fmac_f32_e32 v46, s77, v44
	v_fmac_f32_e32 v47, s77, v45
	v_readlane_b32 s76, v5, 16
	s_waitcnt vmcnt(63)
	v_cvt_pk_bf16_f32 v12, v46, v47
	global_store_dword v3, v12, s[24:25]
	s_add_u32 s24, s24, 0x10000
	s_addc_u32 s25, s25, 0
	v_fmac_f32_e32 v48, s76, v46
	v_fmac_f32_e32 v49, s76, v47
	v_readlane_b32 s77, v5, 17
	s_waitcnt vmcnt(63)
	v_cvt_pk_bf16_f32 v13, v48, v49
	global_store_dword v3, v13, s[24:25]
	s_add_u32 s24, s24, 0x10000
	s_addc_u32 s25, s25, 0
	v_fmac_f32_e32 v50, s77, v48
	v_fmac_f32_e32 v51, s77, v49
	v_readlane_b32 s76, v5, 18
	s_waitcnt vmcnt(63)
	v_cvt_pk_bf16_f32 v14, v50, v51
	global_store_dword v3, v14, s[24:25]
	s_add_u32 s24, s24, 0x10000
	s_addc_u32 s25, s25, 0
	v_fmac_f32_e32 v52, s76, v50
	v_fmac_f32_e32 v53, s76, v51
	v_readlane_b32 s77, v5, 19
	s_waitcnt vmcnt(63)
	v_cvt_pk_bf16_f32 v15, v52, v53
	global_store_dword v3, v15, s[24:25]
	s_add_u32 s24, s24, 0x10000
	s_addc_u32 s25, s25, 0
	v_fmac_f32_e32 v54, s77, v52
	v_fmac_f32_e32 v55, s77, v53
	v_readlane_b32 s76, v5, 20
	s_waitcnt vmcnt(63)
	v_cvt_pk_bf16_f32 v12, v54, v55
	global_store_dword v3, v12, s[24:25]
	s_add_u32 s24, s24, 0x10000
	s_addc_u32 s25, s25, 0
	v_fmac_f32_e32 v56, s76, v54
	v_fmac_f32_e32 v57, s76, v55
	v_readlane_b32 s77, v5, 21
	s_waitcnt vmcnt(63)
	v_cvt_pk_bf16_f32 v13, v56, v57
	global_store_dword v3, v13, s[24:25]
	s_add_u32 s24, s24, 0x10000
	s_addc_u32 s25, s25, 0
	v_fmac_f32_e32 v58, s77, v56
	v_fmac_f32_e32 v59, s77, v57
	v_readlane_b32 s76, v5, 22
	s_waitcnt vmcnt(63)
	v_cvt_pk_bf16_f32 v14, v58, v59
	global_store_dword v3, v14, s[24:25]
	s_add_u32 s24, s24, 0x10000
	s_addc_u32 s25, s25, 0
	v_fmac_f32_e32 v60, s76, v58
	v_fmac_f32_e32 v61, s76, v59
	v_readlane_b32 s77, v5, 23
	s_waitcnt vmcnt(63)
	v_cvt_pk_bf16_f32 v15, v60, v61
	global_store_dword v3, v15, s[24:25]
	s_add_u32 s24, s24, 0x10000
	s_addc_u32 s25, s25, 0
	v_fmac_f32_e32 v62, s77, v60
	v_fmac_f32_e32 v63, s77, v61
	v_readlane_b32 s76, v5, 24
	s_waitcnt vmcnt(63)
	v_cvt_pk_bf16_f32 v12, v62, v63
	global_store_dword v3, v12, s[24:25]
	s_add_u32 s24, s24, 0x10000
	s_addc_u32 s25, s25, 0
	v_fmac_f32_e32 v64, s76, v62
	v_fmac_f32_e32 v65, s76, v63
	v_readlane_b32 s77, v5, 25
	s_waitcnt vmcnt(63)
	v_cvt_pk_bf16_f32 v13, v64, v65
	global_store_dword v3, v13, s[24:25]
	s_add_u32 s24, s24, 0x10000
	s_addc_u32 s25, s25, 0
	v_fmac_f32_e32 v66, s77, v64
	v_fmac_f32_e32 v67, s77, v65
	v_readlane_b32 s76, v5, 26
	s_waitcnt vmcnt(63)
	v_cvt_pk_bf16_f32 v14, v66, v67
	global_store_dword v3, v14, s[24:25]
	s_add_u32 s24, s24, 0x10000
	s_addc_u32 s25, s25, 0
	v_fmac_f32_e32 v68, s76, v66
	v_fmac_f32_e32 v69, s76, v67
	v_readlane_b32 s77, v5, 27
	s_waitcnt vmcnt(63)
	v_cvt_pk_bf16_f32 v15, v68, v69
	global_store_dword v3, v15, s[24:25]
	s_add_u32 s24, s24, 0x10000
	s_addc_u32 s25, s25, 0
	v_fmac_f32_e32 v70, s77, v68
	v_fmac_f32_e32 v71, s77, v69
	v_readlane_b32 s76, v5, 28
	s_waitcnt vmcnt(63)
	v_cvt_pk_bf16_f32 v12, v70, v71
	global_store_dword v3, v12, s[24:25]
	s_add_u32 s24, s24, 0x10000
	s_addc_u32 s25, s25, 0
	v_fmac_f32_e32 v72, s76, v70
	v_fmac_f32_e32 v73, s76, v71
	v_readlane_b32 s77, v5, 29
	s_waitcnt vmcnt(63)
	v_cvt_pk_bf16_f32 v13, v72, v73
	global_store_dword v3, v13, s[24:25]
	s_add_u32 s24, s24, 0x10000
	s_addc_u32 s25, s25, 0
	v_fmac_f32_e32 v74, s77, v72
	v_fmac_f32_e32 v75, s77, v73
	v_readlane_b32 s76, v5, 30
	s_waitcnt vmcnt(63)
	v_cvt_pk_bf16_f32 v14, v74, v75
	global_store_dword v3, v14, s[24:25]
	s_add_u32 s24, s24, 0x10000
	s_addc_u32 s25, s25, 0
	v_fmac_f32_e32 v76, s76, v74
	v_fmac_f32_e32 v77, s76, v75
	v_readlane_b32 s77, v5, 31
	s_waitcnt vmcnt(63)
	v_cvt_pk_bf16_f32 v15, v76, v77
	global_store_dword v3, v15, s[24:25]
	s_add_u32 s24, s24, 0x10000
	s_addc_u32 s25, s25, 0
	v_fmac_f32_e32 v78, s77, v76
	v_fmac_f32_e32 v79, s77, v77
	v_readlane_b32 s76, v5, 32
	s_waitcnt vmcnt(63)
	v_cvt_pk_bf16_f32 v12, v78, v79
	global_store_dword v3, v12, s[24:25]
	s_add_u32 s24, s24, 0x10000
	s_addc_u32 s25, s25, 0
	v_fmac_f32_e32 v80, s76, v78
	v_fmac_f32_e32 v81, s76, v79
	v_readlane_b32 s77, v5, 33
	s_waitcnt vmcnt(63)
	v_cvt_pk_bf16_f32 v13, v80, v81
	global_store_dword v3, v13, s[24:25]
	s_add_u32 s24, s24, 0x10000
	s_addc_u32 s25, s25, 0
	v_fmac_f32_e32 v82, s77, v80
	v_fmac_f32_e32 v83, s77, v81
	v_readlane_b32 s76, v5, 34
	s_waitcnt vmcnt(63)
	v_cvt_pk_bf16_f32 v14, v82, v83
	global_store_dword v3, v14, s[24:25]
	s_add_u32 s24, s24, 0x10000
	s_addc_u32 s25, s25, 0
	v_fmac_f32_e32 v84, s76, v82
	v_fmac_f32_e32 v85, s76, v83
	v_readlane_b32 s77, v5, 35
	s_waitcnt vmcnt(63)
	v_cvt_pk_bf16_f32 v15, v84, v85
	global_store_dword v3, v15, s[24:25]
	s_add_u32 s24, s24, 0x10000
	s_addc_u32 s25, s25, 0
	v_fmac_f32_e32 v86, s77, v84
	v_fmac_f32_e32 v87, s77, v85
	v_readlane_b32 s76, v5, 36
	s_waitcnt vmcnt(63)
	v_cvt_pk_bf16_f32 v12, v86, v87
	global_store_dword v3, v12, s[24:25]
	s_add_u32 s24, s24, 0x10000
	s_addc_u32 s25, s25, 0
	v_fmac_f32_e32 v88, s76, v86
	v_fmac_f32_e32 v89, s76, v87
	v_readlane_b32 s77, v5, 37
	s_waitcnt vmcnt(63)
	v_cvt_pk_bf16_f32 v13, v88, v89
	global_store_dword v3, v13, s[24:25]
	s_add_u32 s24, s24, 0x10000
	s_addc_u32 s25, s25, 0
	v_fmac_f32_e32 v90, s77, v88
	v_fmac_f32_e32 v91, s77, v89
	v_readlane_b32 s76, v5, 38
	s_waitcnt vmcnt(63)
	v_cvt_pk_bf16_f32 v14, v90, v91
	global_store_dword v3, v14, s[24:25]
	s_add_u32 s24, s24, 0x10000
	s_addc_u32 s25, s25, 0
	v_fmac_f32_e32 v92, s76, v90
	v_fmac_f32_e32 v93, s76, v91
	v_readlane_b32 s77, v5, 39
	s_waitcnt vmcnt(63)
	v_cvt_pk_bf16_f32 v15, v92, v93
	global_store_dword v3, v15, s[24:25]
	s_add_u32 s24, s24, 0x10000
	s_addc_u32 s25, s25, 0
	v_fmac_f32_e32 v94, s77, v92
	v_fmac_f32_e32 v95, s77, v93
	v_readlane_b32 s76, v5, 40
	s_waitcnt vmcnt(63)
	v_cvt_pk_bf16_f32 v12, v94, v95
	global_store_dword v3, v12, s[24:25]
	s_add_u32 s24, s24, 0x10000
	s_addc_u32 s25, s25, 0
	v_fmac_f32_e32 v96, s76, v94
	v_fmac_f32_e32 v97, s76, v95
	v_readlane_b32 s77, v5, 41
	s_waitcnt vmcnt(63)
	v_cvt_pk_bf16_f32 v13, v96, v97
	global_store_dword v3, v13, s[24:25]
	s_add_u32 s24, s24, 0x10000
	s_addc_u32 s25, s25, 0
	v_fmac_f32_e32 v98, s77, v96
	v_fmac_f32_e32 v99, s77, v97
	v_readlane_b32 s76, v5, 42
	s_waitcnt vmcnt(63)
	v_cvt_pk_bf16_f32 v14, v98, v99
	global_store_dword v3, v14, s[24:25]
	s_add_u32 s24, s24, 0x10000
	s_addc_u32 s25, s25, 0
	v_fmac_f32_e32 v100, s76, v98
	v_fmac_f32_e32 v101, s76, v99
	v_readlane_b32 s77, v5, 43
	s_waitcnt vmcnt(63)
	v_cvt_pk_bf16_f32 v15, v100, v101
	global_store_dword v3, v15, s[24:25]
	s_add_u32 s24, s24, 0x10000
	s_addc_u32 s25, s25, 0
	v_fmac_f32_e32 v102, s77, v100
	v_fmac_f32_e32 v103, s77, v101
	v_readlane_b32 s76, v5, 44
	s_waitcnt vmcnt(63)
	v_cvt_pk_bf16_f32 v12, v102, v103
	global_store_dword v3, v12, s[24:25]
	s_add_u32 s24, s24, 0x10000
	s_addc_u32 s25, s25, 0
	v_fmac_f32_e32 v104, s76, v102
	v_fmac_f32_e32 v105, s76, v103
	v_readlane_b32 s77, v5, 45
	s_waitcnt vmcnt(63)
	v_cvt_pk_bf16_f32 v13, v104, v105
	global_store_dword v3, v13, s[24:25]
	s_add_u32 s24, s24, 0x10000
	s_addc_u32 s25, s25, 0
	v_fmac_f32_e32 v106, s77, v104
	v_fmac_f32_e32 v107, s77, v105
	v_readlane_b32 s76, v5, 46
	s_waitcnt vmcnt(63)
	v_cvt_pk_bf16_f32 v14, v106, v107
	global_store_dword v3, v14, s[24:25]
	s_add_u32 s24, s24, 0x10000
	s_addc_u32 s25, s25, 0
	v_fmac_f32_e32 v108, s76, v106
	v_fmac_f32_e32 v109, s76, v107
	v_readlane_b32 s77, v5, 47
	s_waitcnt vmcnt(63)
	v_cvt_pk_bf16_f32 v15, v108, v109
	global_store_dword v3, v15, s[24:25]
	s_add_u32 s24, s24, 0x10000
	s_addc_u32 s25, s25, 0
	v_fmac_f32_e32 v110, s77, v108
	v_fmac_f32_e32 v111, s77, v109
	v_readlane_b32 s76, v5, 48
	s_waitcnt vmcnt(63)
	v_cvt_pk_bf16_f32 v12, v110, v111
	global_store_dword v3, v12, s[24:25]
	s_add_u32 s24, s24, 0x10000
	s_addc_u32 s25, s25, 0
	v_fmac_f32_e32 v112, s76, v110
	v_fmac_f32_e32 v113, s76, v111
	v_readlane_b32 s77, v5, 49
	s_waitcnt vmcnt(63)
	v_cvt_pk_bf16_f32 v13, v112, v113
	global_store_dword v3, v13, s[24:25]
	s_add_u32 s24, s24, 0x10000
	s_addc_u32 s25, s25, 0
	v_fmac_f32_e32 v114, s77, v112
	v_fmac_f32_e32 v115, s77, v113
	v_readlane_b32 s76, v5, 50
	s_waitcnt vmcnt(63)
	v_cvt_pk_bf16_f32 v14, v114, v115
	global_store_dword v3, v14, s[24:25]
	s_add_u32 s24, s24, 0x10000
	s_addc_u32 s25, s25, 0
	v_fmac_f32_e32 v116, s76, v114
	v_fmac_f32_e32 v117, s76, v115
	v_readlane_b32 s77, v5, 51
	s_waitcnt vmcnt(63)
	v_cvt_pk_bf16_f32 v15, v116, v117
	global_store_dword v3, v15, s[24:25]
	s_add_u32 s24, s24, 0x10000
	s_addc_u32 s25, s25, 0
	v_fmac_f32_e32 v118, s77, v116
	v_fmac_f32_e32 v119, s77, v117
	v_readlane_b32 s76, v5, 52
	s_waitcnt vmcnt(63)
	v_cvt_pk_bf16_f32 v12, v118, v119
	global_store_dword v3, v12, s[24:25]
	s_add_u32 s24, s24, 0x10000
	s_addc_u32 s25, s25, 0
	v_fmac_f32_e32 v120, s76, v118
	v_fmac_f32_e32 v121, s76, v119
	v_readlane_b32 s77, v5, 53
	s_waitcnt vmcnt(63)
	v_cvt_pk_bf16_f32 v13, v120, v121
	global_store_dword v3, v13, s[24:25]
	s_add_u32 s24, s24, 0x10000
	s_addc_u32 s25, s25, 0
	v_fmac_f32_e32 v122, s77, v120
	v_fmac_f32_e32 v123, s77, v121
	v_readlane_b32 s76, v5, 54
	s_waitcnt vmcnt(63)
	v_cvt_pk_bf16_f32 v14, v122, v123
	global_store_dword v3, v14, s[24:25]
	s_add_u32 s24, s24, 0x10000
	s_addc_u32 s25, s25, 0
	v_fmac_f32_e32 v124, s76, v122
	v_fmac_f32_e32 v125, s76, v123
	v_readlane_b32 s77, v5, 55
	s_waitcnt vmcnt(63)
	v_cvt_pk_bf16_f32 v15, v124, v125
	global_store_dword v3, v15, s[24:25]
	s_add_u32 s24, s24, 0x10000
	s_addc_u32 s25, s25, 0
	v_fmac_f32_e32 v126, s77, v124
	v_fmac_f32_e32 v127, s77, v125
	v_readlane_b32 s76, v5, 56
	s_waitcnt vmcnt(63)
	v_cvt_pk_bf16_f32 v12, v126, v127
	global_store_dword v3, v12, s[24:25]
	s_add_u32 s24, s24, 0x10000
	s_addc_u32 s25, s25, 0
	v_fmac_f32_e32 v128, s76, v126
	v_fmac_f32_e32 v129, s76, v127
	v_readlane_b32 s77, v5, 57
	s_waitcnt vmcnt(63)
	v_cvt_pk_bf16_f32 v13, v128, v129
	global_store_dword v3, v13, s[24:25]
	s_add_u32 s24, s24, 0x10000
	s_addc_u32 s25, s25, 0
	v_fmac_f32_e32 v130, s77, v128
	v_fmac_f32_e32 v131, s77, v129
	v_readlane_b32 s76, v5, 58
	s_waitcnt vmcnt(63)
	v_cvt_pk_bf16_f32 v14, v130, v131
	global_store_dword v3, v14, s[24:25]
	s_add_u32 s24, s24, 0x10000
	s_addc_u32 s25, s25, 0
	v_fmac_f32_e32 v132, s76, v130
	v_fmac_f32_e32 v133, s76, v131
	v_readlane_b32 s77, v5, 59
	s_waitcnt vmcnt(63)
	v_cvt_pk_bf16_f32 v15, v132, v133
	global_store_dword v3, v15, s[24:25]
	s_add_u32 s24, s24, 0x10000
	s_addc_u32 s25, s25, 0
	v_fmac_f32_e32 v134, s77, v132
	v_fmac_f32_e32 v135, s77, v133
	v_readlane_b32 s76, v5, 60
	s_waitcnt vmcnt(63)
	v_cvt_pk_bf16_f32 v12, v134, v135
	global_store_dword v3, v12, s[24:25]
	s_add_u32 s24, s24, 0x10000
	s_addc_u32 s25, s25, 0
	v_fmac_f32_e32 v136, s76, v134
	v_fmac_f32_e32 v137, s76, v135
	v_readlane_b32 s77, v5, 61
	s_waitcnt vmcnt(63)
	v_cvt_pk_bf16_f32 v13, v136, v137
	global_store_dword v3, v13, s[24:25]
	s_add_u32 s24, s24, 0x10000
	s_addc_u32 s25, s25, 0
	v_fmac_f32_e32 v138, s77, v136
	v_fmac_f32_e32 v139, s77, v137
	v_readlane_b32 s76, v5, 62
	s_waitcnt vmcnt(63)
	v_cvt_pk_bf16_f32 v14, v138, v139
	global_store_dword v3, v14, s[24:25]
	s_add_u32 s24, s24, 0x10000
	s_addc_u32 s25, s25, 0
	v_fmac_f32_e32 v140, s76, v138
	v_fmac_f32_e32 v141, s76, v139
	v_readlane_b32 s77, v5, 63
	s_waitcnt vmcnt(63)
	v_cvt_pk_bf16_f32 v15, v140, v141
	global_store_dword v3, v15, s[24:25]
	s_add_u32 s24, s24, 0x10000
	s_addc_u32 s25, s25, 0
	v_fmac_f32_e32 v142, s77, v140
	v_fmac_f32_e32 v143, s77, v141
	global_store_dwordx2 v2, v[142:143], s[2:3]
	s_branch .LBB0_440
